# merged X+S scan stage with s_setprio 3 around the in-register DPP solve on waves 4-7
# speedup vs baseline: 1.0098x; 1.0084x over previous
.Lsx0_d:
	s_setprio 3
	s_waitcnt lgkmcnt(0)
	s_nop 6
	v_fmac_f32_dpp v30, v30, v80 row_newbcast:0 row_mask:0xf bank_mask:0xf
	v_fmac_f32_dpp v31, v31, v80 row_newbcast:0 row_mask:0xf bank_mask:0xf
	v_fmac_f32_dpp v32, v32, v80 row_newbcast:0 row_mask:0xf bank_mask:0xf
	v_fmac_f32_dpp v33, v33, v80 row_newbcast:0 row_mask:0xf bank_mask:0xf
	v_fmac_f32_dpp v30, v30, v81 row_newbcast:1 row_mask:0xf bank_mask:0xf
	v_fmac_f32_dpp v31, v31, v81 row_newbcast:1 row_mask:0xf bank_mask:0xf
	v_fmac_f32_dpp v32, v32, v81 row_newbcast:1 row_mask:0xf bank_mask:0xf
	v_fmac_f32_dpp v33, v33, v81 row_newbcast:1 row_mask:0xf bank_mask:0xf
	v_fmac_f32_dpp v30, v30, v82 row_newbcast:2 row_mask:0xf bank_mask:0xf
	v_fmac_f32_dpp v31, v31, v82 row_newbcast:2 row_mask:0xf bank_mask:0xf
	v_fmac_f32_dpp v32, v32, v82 row_newbcast:2 row_mask:0xf bank_mask:0xf
	v_fmac_f32_dpp v33, v33, v82 row_newbcast:2 row_mask:0xf bank_mask:0xf
	v_fmac_f32_dpp v30, v30, v83 row_newbcast:3 row_mask:0xf bank_mask:0xf
	v_fmac_f32_dpp v31, v31, v83 row_newbcast:3 row_mask:0xf bank_mask:0xf
	v_fmac_f32_dpp v32, v32, v83 row_newbcast:3 row_mask:0xf bank_mask:0xf
	v_fmac_f32_dpp v33, v33, v83 row_newbcast:3 row_mask:0xf bank_mask:0xf
	v_fmac_f32_dpp v30, v30, v84 row_newbcast:4 row_mask:0xf bank_mask:0xf
	v_fmac_f32_dpp v31, v31, v84 row_newbcast:4 row_mask:0xf bank_mask:0xf
	v_fmac_f32_dpp v32, v32, v84 row_newbcast:4 row_mask:0xf bank_mask:0xf
	v_fmac_f32_dpp v33, v33, v84 row_newbcast:4 row_mask:0xf bank_mask:0xf
	v_fmac_f32_dpp v30, v30, v85 row_newbcast:5 row_mask:0xf bank_mask:0xf
	v_fmac_f32_dpp v31, v31, v85 row_newbcast:5 row_mask:0xf bank_mask:0xf
	v_fmac_f32_dpp v32, v32, v85 row_newbcast:5 row_mask:0xf bank_mask:0xf
	v_fmac_f32_dpp v33, v33, v85 row_newbcast:5 row_mask:0xf bank_mask:0xf
	v_fmac_f32_dpp v30, v30, v86 row_newbcast:6 row_mask:0xf bank_mask:0xf
	v_fmac_f32_dpp v31, v31, v86 row_newbcast:6 row_mask:0xf bank_mask:0xf
	v_fmac_f32_dpp v32, v32, v86 row_newbcast:6 row_mask:0xf bank_mask:0xf
	v_fmac_f32_dpp v33, v33, v86 row_newbcast:6 row_mask:0xf bank_mask:0xf
	v_fmac_f32_dpp v30, v30, v87 row_newbcast:7 row_mask:0xf bank_mask:0xf
	v_fmac_f32_dpp v31, v31, v87 row_newbcast:7 row_mask:0xf bank_mask:0xf
	v_fmac_f32_dpp v32, v32, v87 row_newbcast:7 row_mask:0xf bank_mask:0xf
	v_fmac_f32_dpp v33, v33, v87 row_newbcast:7 row_mask:0xf bank_mask:0xf
	v_fmac_f32_dpp v30, v30, v88 row_newbcast:8 row_mask:0xf bank_mask:0xf
	v_fmac_f32_dpp v31, v31, v88 row_newbcast:8 row_mask:0xf bank_mask:0xf
	v_fmac_f32_dpp v32, v32, v88 row_newbcast:8 row_mask:0xf bank_mask:0xf
	v_fmac_f32_dpp v33, v33, v88 row_newbcast:8 row_mask:0xf bank_mask:0xf
	v_fmac_f32_dpp v30, v30, v89 row_newbcast:9 row_mask:0xf bank_mask:0xf
	v_fmac_f32_dpp v31, v31, v89 row_newbcast:9 row_mask:0xf bank_mask:0xf
	v_fmac_f32_dpp v32, v32, v89 row_newbcast:9 row_mask:0xf bank_mask:0xf
	v_fmac_f32_dpp v33, v33, v89 row_newbcast:9 row_mask:0xf bank_mask:0xf
	v_fmac_f32_dpp v30, v30, v90 row_newbcast:10 row_mask:0xf bank_mask:0xf
	v_fmac_f32_dpp v31, v31, v90 row_newbcast:10 row_mask:0xf bank_mask:0xf
	v_fmac_f32_dpp v32, v32, v90 row_newbcast:10 row_mask:0xf bank_mask:0xf
	v_fmac_f32_dpp v33, v33, v90 row_newbcast:10 row_mask:0xf bank_mask:0xf
	v_fmac_f32_dpp v30, v30, v91 row_newbcast:11 row_mask:0xf bank_mask:0xf
	v_fmac_f32_dpp v31, v31, v91 row_newbcast:11 row_mask:0xf bank_mask:0xf
	v_fmac_f32_dpp v32, v32, v91 row_newbcast:11 row_mask:0xf bank_mask:0xf
	v_fmac_f32_dpp v33, v33, v91 row_newbcast:11 row_mask:0xf bank_mask:0xf
	v_fmac_f32_dpp v30, v30, v92 row_newbcast:12 row_mask:0xf bank_mask:0xf
	v_fmac_f32_dpp v31, v31, v92 row_newbcast:12 row_mask:0xf bank_mask:0xf
	v_fmac_f32_dpp v32, v32, v92 row_newbcast:12 row_mask:0xf bank_mask:0xf
	v_fmac_f32_dpp v33, v33, v92 row_newbcast:12 row_mask:0xf bank_mask:0xf
	v_fmac_f32_dpp v30, v30, v93 row_newbcast:13 row_mask:0xf bank_mask:0xf
	v_fmac_f32_dpp v31, v31, v93 row_newbcast:13 row_mask:0xf bank_mask:0xf
	v_fmac_f32_dpp v32, v32, v93 row_newbcast:13 row_mask:0xf bank_mask:0xf
	v_fmac_f32_dpp v33, v33, v93 row_newbcast:13 row_mask:0xf bank_mask:0xf
	v_fmac_f32_dpp v30, v30, v94 row_newbcast:14 row_mask:0xf bank_mask:0xf
	v_fmac_f32_dpp v31, v31, v94 row_newbcast:14 row_mask:0xf bank_mask:0xf
	v_fmac_f32_dpp v32, v32, v94 row_newbcast:14 row_mask:0xf bank_mask:0xf
	v_fmac_f32_dpp v33, v33, v94 row_newbcast:14 row_mask:0xf bank_mask:0xf
	v_lshrrev_b32_e32 v82, 6, v198
	v_mul_u32_u24_e32 v82, 0x500, v82
	v_mad_u32_u24 v82, v145, 20, v82
	v_and_b32_e32 v83, 15, v198
	v_lshl_add_u32 v82, v83, 1, v82
	v_add_u32_e32 v82, 0x10a00, v82
	v_cvt_pk_bf16_f32 v80, v30, v31
	v_cvt_pk_bf16_f32 v81, v32, v33
	ds_write_b16 v82, v80 offset:0
	ds_write_b16_d16_hi v82, v80 offset:80
	ds_write_b16 v82, v81 offset:160
	ds_write_b16_d16_hi v82, v81 offset:240
	s_setprio 0

.Lsx1_c:
	s_or_b64 exec, exec, s[74:75]
	v_mov_b32_e32 v22, 0
	v_mov_b32_e32 v23, 0
	v_mov_b32_e32 v24, 0
	v_mov_b32_e32 v25, 0
	s_and_saveexec_b64 s[74:75], s[56:57]
	s_cbranch_execz .LBB0_432
	ds_read_b128 v[48:51], v174
	ds_read_b128 v[60:63], v192 offset:51456
	ds_read_b128 v[52:55], v174 offset:64
	ds_read_b128 v[64:67], v192 offset:51520
	ds_read_b128 v[56:59], v175 offset:5120
	ds_read_b128 v[68:71], v199
	ds_read_b128 v[72:75], v192 offset:60672
	ds_read_b128 v[76:79], v192 offset:60736
	ds_read_b128 v[80:83], v151
	ds_read_b128 v[84:87], v151 offset:16
	ds_read_b128 v[88:91], v151 offset:32
	ds_read_b128 v[92:95], v151 offset:48
	s_waitcnt lgkmcnt(10)
	v_mfma_f32_16x16x32_bf16 v[30:33], v[48:51], v[60:63], 0
	s_waitcnt lgkmcnt(8)
	v_mfma_f32_16x16x32_bf16 v[30:33], v[52:55], v[64:67], v[30:33]
	s_waitcnt lgkmcnt(6)
	v_mfma_f32_16x16x32_bf16 v[30:33], v[56:59], v[68:71], v[30:33]
	s_waitcnt lgkmcnt(5)
	v_mfma_f32_16x16x32_bf16 v[22:25], v[48:51], v[72:75], 0
	s_waitcnt lgkmcnt(4)
	v_mfma_f32_16x16x32_bf16 v[22:25], v[52:55], v[76:79], v[22:25]
	v_cvt_pk_bf16_f32 v240, v236, v237
	global_store_dword v[238:239], v240, off
	s_setprio 3
	s_waitcnt lgkmcnt(0)
	s_nop 6
	v_fmac_f32_dpp v30, v30, v80 row_newbcast:0 row_mask:0xf bank_mask:0xf
	v_fmac_f32_dpp v31, v31, v80 row_newbcast:0 row_mask:0xf bank_mask:0xf
	v_fmac_f32_dpp v32, v32, v80 row_newbcast:0 row_mask:0xf bank_mask:0xf
	v_fmac_f32_dpp v33, v33, v80 row_newbcast:0 row_mask:0xf bank_mask:0xf
	v_fmac_f32_dpp v30, v30, v81 row_newbcast:1 row_mask:0xf bank_mask:0xf
	v_fmac_f32_dpp v31, v31, v81 row_newbcast:1 row_mask:0xf bank_mask:0xf
	v_fmac_f32_dpp v32, v32, v81 row_newbcast:1 row_mask:0xf bank_mask:0xf
	v_fmac_f32_dpp v33, v33, v81 row_newbcast:1 row_mask:0xf bank_mask:0xf
	v_fmac_f32_dpp v30, v30, v82 row_newbcast:2 row_mask:0xf bank_mask:0xf
	v_fmac_f32_dpp v31, v31, v82 row_newbcast:2 row_mask:0xf bank_mask:0xf
	v_fmac_f32_dpp v32, v32, v82 row_newbcast:2 row_mask:0xf bank_mask:0xf
	v_fmac_f32_dpp v33, v33, v82 row_newbcast:2 row_mask:0xf bank_mask:0xf
	v_fmac_f32_dpp v30, v30, v83 row_newbcast:3 row_mask:0xf bank_mask:0xf
	v_fmac_f32_dpp v31, v31, v83 row_newbcast:3 row_mask:0xf bank_mask:0xf
	v_fmac_f32_dpp v32, v32, v83 row_newbcast:3 row_mask:0xf bank_mask:0xf
	v_fmac_f32_dpp v33, v33, v83 row_newbcast:3 row_mask:0xf bank_mask:0xf
	v_fmac_f32_dpp v30, v30, v84 row_newbcast:4 row_mask:0xf bank_mask:0xf
	v_fmac_f32_dpp v31, v31, v84 row_newbcast:4 row_mask:0xf bank_mask:0xf
	v_fmac_f32_dpp v32, v32, v84 row_newbcast:4 row_mask:0xf bank_mask:0xf
	v_fmac_f32_dpp v33, v33, v84 row_newbcast:4 row_mask:0xf bank_mask:0xf
	v_fmac_f32_dpp v30, v30, v85 row_newbcast:5 row_mask:0xf bank_mask:0xf
	v_fmac_f32_dpp v31, v31, v85 row_newbcast:5 row_mask:0xf bank_mask:0xf
	v_fmac_f32_dpp v32, v32, v85 row_newbcast:5 row_mask:0xf bank_mask:0xf
	v_fmac_f32_dpp v33, v33, v85 row_newbcast:5 row_mask:0xf bank_mask:0xf
	v_fmac_f32_dpp v30, v30, v86 row_newbcast:6 row_mask:0xf bank_mask:0xf
	v_fmac_f32_dpp v31, v31, v86 row_newbcast:6 row_mask:0xf bank_mask:0xf
	v_fmac_f32_dpp v32, v32, v86 row_newbcast:6 row_mask:0xf bank_mask:0xf
	v_fmac_f32_dpp v33, v33, v86 row_newbcast:6 row_mask:0xf bank_mask:0xf
	v_fmac_f32_dpp v30, v30, v87 row_newbcast:7 row_mask:0xf bank_mask:0xf
	v_fmac_f32_dpp v31, v31, v87 row_newbcast:7 row_mask:0xf bank_mask:0xf
	v_fmac_f32_dpp v32, v32, v87 row_newbcast:7 row_mask:0xf bank_mask:0xf
	v_fmac_f32_dpp v33, v33, v87 row_newbcast:7 row_mask:0xf bank_mask:0xf
	v_fmac_f32_dpp v30, v30, v88 row_newbcast:8 row_mask:0xf bank_mask:0xf
	v_fmac_f32_dpp v31, v31, v88 row_newbcast:8 row_mask:0xf bank_mask:0xf
	v_fmac_f32_dpp v32, v32, v88 row_newbcast:8 row_mask:0xf bank_mask:0xf
	v_fmac_f32_dpp v33, v33, v88 row_newbcast:8 row_mask:0xf bank_mask:0xf
	v_fmac_f32_dpp v30, v30, v89 row_newbcast:9 row_mask:0xf bank_mask:0xf
	v_fmac_f32_dpp v31, v31, v89 row_newbcast:9 row_mask:0xf bank_mask:0xf
	v_fmac_f32_dpp v32, v32, v89 row_newbcast:9 row_mask:0xf bank_mask:0xf
	v_fmac_f32_dpp v33, v33, v89 row_newbcast:9 row_mask:0xf bank_mask:0xf
	v_fmac_f32_dpp v30, v30, v90 row_newbcast:10 row_mask:0xf bank_mask:0xf
	v_fmac_f32_dpp v31, v31, v90 row_newbcast:10 row_mask:0xf bank_mask:0xf
	v_fmac_f32_dpp v32, v32, v90 row_newbcast:10 row_mask:0xf bank_mask:0xf
	v_fmac_f32_dpp v33, v33, v90 row_newbcast:10 row_mask:0xf bank_mask:0xf
	v_fmac_f32_dpp v30, v30, v91 row_newbcast:11 row_mask:0xf bank_mask:0xf
	v_fmac_f32_dpp v31, v31, v91 row_newbcast:11 row_mask:0xf bank_mask:0xf
	v_fmac_f32_dpp v32, v32, v91 row_newbcast:11 row_mask:0xf bank_mask:0xf
	v_fmac_f32_dpp v33, v33, v91 row_newbcast:11 row_mask:0xf bank_mask:0xf
	v_fmac_f32_dpp v30, v30, v92 row_newbcast:12 row_mask:0xf bank_mask:0xf
	v_fmac_f32_dpp v31, v31, v92 row_newbcast:12 row_mask:0xf bank_mask:0xf
	v_fmac_f32_dpp v32, v32, v92 row_newbcast:12 row_mask:0xf bank_mask:0xf
	v_fmac_f32_dpp v33, v33, v92 row_newbcast:12 row_mask:0xf bank_mask:0xf
	v_fmac_f32_dpp v30, v30, v93 row_newbcast:13 row_mask:0xf bank_mask:0xf
	v_fmac_f32_dpp v31, v31, v93 row_newbcast:13 row_mask:0xf bank_mask:0xf
	v_fmac_f32_dpp v32, v32, v93 row_newbcast:13 row_mask:0xf bank_mask:0xf
	v_fmac_f32_dpp v33, v33, v93 row_newbcast:13 row_mask:0xf bank_mask:0xf
	v_fmac_f32_dpp v30, v30, v94 row_newbcast:14 row_mask:0xf bank_mask:0xf
	v_fmac_f32_dpp v31, v31, v94 row_newbcast:14 row_mask:0xf bank_mask:0xf
	v_fmac_f32_dpp v32, v32, v94 row_newbcast:14 row_mask:0xf bank_mask:0xf
	v_fmac_f32_dpp v33, v33, v94 row_newbcast:14 row_mask:0xf bank_mask:0xf
	v_lshrrev_b32_e32 v82, 6, v198
	v_mul_u32_u24_e32 v82, 0x500, v82
	v_mad_u32_u24 v82, v145, 20, v82
	v_and_b32_e32 v83, 15, v198
	v_lshl_add_u32 v82, v83, 1, v82
	v_add_u32_e32 v82, 0x10a00, v82
	v_cvt_pk_bf16_f32 v80, v30, v31
	v_cvt_pk_bf16_f32 v81, v32, v33
	ds_write_b16 v82, v80 offset:5120
	ds_write_b16_d16_hi v82, v80 offset:5200
	ds_write_b16 v82, v81 offset:5280
	ds_write_b16_d16_hi v82, v81 offset:5360
	s_setprio 0
